# S3 pointwise-conv GEMM K-loop: LDS-DMA loads use SGPR base + 32-bit lane offset (no per-load 64-bit VALU address adds), on top of the peel
# baseline (speedup 1.0000x reference)
; #define PG8_STAGE(bufoff, gbase, voff) do { _Pragma("unroll") for (int _i = 0; _i < 2; ++_i) \
;         __builtin_amdgcn_global_load_lds((const unsigned*)((const char*)(gbase) + (voff)[_i]), (PG8_LAS unsigned*)(lds + (bufoff) + ldsw + _i * 8192), 16, 0, 0); } while (0)
; #define PG8_LDA(dst, b, h) do { _Pragma("unroll") for (int m = 0; m < 4; ++m) _Pragma("unroll") for (int k = 0; k < 2; ++k) dst[m][k] = *(const PG8_LAS bf16x8*)(lds + PG8_SA(b, h) + aoff + m * 2048 + k * 1024); } while (0)
; #define PG8_LDB(dst, b, h) do { _Pragma("unroll") for (int n = 0; n < 2; ++n) _Pragma("unroll") for (int k = 0; k < 2; ++k) dst[n][k] = *(const PG8_LAS bf16x8*)(lds + PG8_SB(b, h) + boff + n * 2048 + k * 1024); } while (0)
; #define PG8_MMA(ai, bj, At, Bt) do { __builtin_amdgcn_s_setprio(1); _Pragma("unroll") for (int m = 0; m < 4; ++m) _Pragma("unroll") for (int n = 0; n < 2; ++n) _Pragma("unroll") for (int k = 0; k < 2; ++k) \
;         acc[ai][bj][m][n] = __builtin_amdgcn_mfma_f32_16x16x32_bf16(Bt[n][k], At[m][k], acc[ai][bj][m][n], 0, 0, 0); __builtin_amdgcn_s_setprio(0); } while (0)
; #define PG8_WAIT_V(n) asm volatile("s_waitcnt vmcnt(" #n ")" ::: "memory")
; #define PG8_BAR __builtin_amdgcn_s_barrier()
; template <class Epi, class Sched, bool ALIGN_EPI = false, bool SP2 = false>
; __device__ __forceinline__ void gemm_phase(PG8_LAS unsigned char* lds, const Gemm g, const Sched& S, const Epi& E) {
;     ...
;         for (int t = 0; t < nt; t += 2) {
;             const bool last = (t == nt - 2);
;             const char* a1 = cA + (size_t)(t + 1) * kstep;
;             const char* a2 = last ? nA : cA + (size_t)(t + 2) * kstep; const char* b2 = last ? nB : cB + (size_t)(t + 2) * kstep;
;             const char* a3 = a2 + kstep; const char* b3 = b2 + kstep;
;             if (last && has_next) S.a_ready(nxt);
;             if constexpr (SP2) {
;             PG8_LDB(B0, 0, 0); PG8_LDB(B1, 0, 1); PG8_SCHED; PG8_LDA(At, 0, 0); PG8_STAGE(PG8_SA(1, 1), a1 + hstep, voffA);
;             PG8_WAIT_V(8); PG8_WAIT_L(0); PG8_BAR; PG8_MMA(0, 0, At, B0); PG8_MMA(0, 1, At, B1); PG8_BAR; PG8_SCHED;
;             PG8_LDA(At, 0, 1); PG8_STAGE(PG8_SB(0, 0), b2, voffB); PG8_STAGE(PG8_SB(0, 1), b2 + hstep, voffB); PG8_STAGE(PG8_SA(0, 0), a2, voffA);
;             PG8_WAIT_V(8); PG8_WAIT_L(0); PG8_BAR; PG8_MMA(1, 0, At, B0); PG8_MMA(1, 1, At, B1); PG8_BAR; PG8_SCHED;
.LBB0_744:
	s_ashr_i32 s9, s8, 31
	s_lshl_b64 s[12:13], s[8:9], 18
	v_readlane_b32 s16, v253, 31
	v_readlane_b32 s17, v253, 32
	s_add_u32 s12, s16, s12
	s_addc_u32 s13, s17, s13
	s_and_b64 s[16:17], s[14:15], exec
	s_cselect_b32 s9, s13, s1
	s_cselect_b32 s35, s12, s0
	s_ashr_i32 s11, s10, 31
	s_lshl_b64 s[16:17], s[10:11], 18
	s_add_u32 s16, s23, s16
	s_addc_u32 s17, s24, s17
	s_and_b64 s[20:21], s[14:15], exec
	s_cselect_b32 s11, s17, s19
	s_cselect_b32 s36, s16, s18
	s_add_u32 s0, s0, 0x20080
	s_addc_u32 s1, s1, 0
	s_add_u32 s37, s18, 0x100
	s_addc_u32 s38, s19, 0
	s_mov_b32 s39, -2
	s_add_u32 s18, s0, 0xfffe0080
	s_addc_u32 s19, s1, -1
	s_add_i32 s40, 0, 0x10000
	s_cmp_eq_u32 s39, 4
	s_cselect_b32 s21, s9, s19
	s_cselect_b32 s20, s35, s18
	s_cselect_b32 s19, s11, s38
	s_cselect_b32 s18, s36, s37
	s_add_i32 s42, 0, 0x14000
	v_add_u32_e32 v142, s40, v161
	v_add_u32_e32 v177, s42, v161
	ds_read_b128 v[130:133], v142
	ds_read_b128 v[134:137], v142 offset:1024
	ds_read_b128 v[138:141], v142 offset:2048
	ds_read_b128 v[142:145], v142 offset:3072
	ds_read_b128 v[156:159], v177
	ds_read_b128 v[164:167], v177 offset:1024
	ds_read_b128 v[172:175], v177 offset:2048
	ds_read_b128 v[178:181], v177 offset:3072
	s_add_i32 m0, s25, 0xc000
	ds_read_b128 v[182:185], v176
	ds_read_b128 v[200:203], v176 offset:1024
	ds_read_b128 v[204:207], v176 offset:2048
	ds_read_b128 v[208:211], v176 offset:3072
	ds_read_b128 v[212:215], v176 offset:4096
	ds_read_b128 v[216:219], v176 offset:5120
	ds_read_b128 v[220:223], v176 offset:6144
	ds_read_b128 v[224:227], v176 offset:7168
	global_load_lds_dwordx4 v152, s[0:1]
	s_add_i32 m0, s25, 0xe000
	s_nop 0
	global_load_lds_dwordx4 v154, s[0:1]
	s_waitcnt vmcnt(8)
	s_waitcnt lgkmcnt(0)
	s_barrier
	s_setprio 1
	s_waitcnt lgkmcnt(0)
	v_mfma_f32_16x16x32_bf16 v[126:129], v[130:133], v[182:185], 0
	v_mfma_f32_16x16x32_bf16 v[122:125], v[138:141], v[182:185], 0
	v_mfma_f32_16x16x32_bf16 v[114:117], v[130:133], v[204:207], 0
	v_mfma_f32_16x16x32_bf16 v[106:109], v[138:141], v[204:207], 0
	v_mfma_f32_16x16x32_bf16 v[98:101], v[130:133], v[212:215], 0
	v_mfma_f32_16x16x32_bf16 v[90:93], v[138:141], v[212:215], 0
	v_mfma_f32_16x16x32_bf16 v[82:85], v[130:133], v[220:223], 0
	v_mfma_f32_16x16x32_bf16 v[74:77], v[138:141], v[220:223], 0
	v_mfma_f32_16x16x32_bf16 v[126:129], v[134:137], v[200:203], v[126:129]
	v_mfma_f32_16x16x32_bf16 v[122:125], v[142:145], v[200:203], v[122:125]
	v_mfma_f32_16x16x32_bf16 v[114:117], v[134:137], v[208:211], v[114:117]
	v_mfma_f32_16x16x32_bf16 v[106:109], v[142:145], v[208:211], v[106:109]
	v_mfma_f32_16x16x32_bf16 v[98:101], v[134:137], v[216:219], v[98:101]
	v_mfma_f32_16x16x32_bf16 v[90:93], v[142:145], v[216:219], v[90:93]
	v_mfma_f32_16x16x32_bf16 v[82:85], v[134:137], v[224:227], v[82:85]
	v_mfma_f32_16x16x32_bf16 v[74:77], v[142:145], v[224:227], v[74:77]
	s_setprio 0
	s_setprio 1
	v_mfma_f32_16x16x32_bf16 v[118:121], v[156:159], v[182:185], 0
	v_mfma_f32_16x16x32_bf16 v[110:113], v[172:175], v[182:185], 0
	v_mfma_f32_16x16x32_bf16 v[102:105], v[156:159], v[204:207], 0
	v_mfma_f32_16x16x32_bf16 v[94:97], v[172:175], v[204:207], 0
	v_mfma_f32_16x16x32_bf16 v[86:89], v[156:159], v[212:215], 0
	v_mfma_f32_16x16x32_bf16 v[78:81], v[172:175], v[212:215], 0
	v_mfma_f32_16x16x32_bf16 v[70:73], v[156:159], v[220:223], 0
	v_mfma_f32_16x16x32_bf16 v[66:69], v[172:175], v[220:223], 0
	v_mfma_f32_16x16x32_bf16 v[118:121], v[164:167], v[200:203], v[118:121]
	v_mfma_f32_16x16x32_bf16 v[110:113], v[178:181], v[200:203], v[110:113]
	v_mfma_f32_16x16x32_bf16 v[102:105], v[164:167], v[208:211], v[102:105]
	v_mfma_f32_16x16x32_bf16 v[94:97], v[178:181], v[208:211], v[94:97]
	v_mfma_f32_16x16x32_bf16 v[86:89], v[164:167], v[216:219], v[86:89]
	v_mfma_f32_16x16x32_bf16 v[78:81], v[178:181], v[216:219], v[78:81]
	v_mfma_f32_16x16x32_bf16 v[70:73], v[164:167], v[224:227], v[70:73]
	v_mfma_f32_16x16x32_bf16 v[66:69], v[178:181], v[224:227], v[66:69]
	s_setprio 0
	s_barrier
	s_add_i32 s40, s40, s22
	s_add_u32 s84, s18, s44
	s_addc_u32 s85, s19, s45
	s_mov_b32 m0, s40
	ds_read_b128 v[182:185], v176 offset:16384
	ds_read_b128 v[200:203], v176 offset:17408
	ds_read_b128 v[204:207], v176 offset:18432
	ds_read_b128 v[208:211], v176 offset:19456
	ds_read_b128 v[212:215], v176 offset:20480
	ds_read_b128 v[216:219], v176 offset:21504
	ds_read_b128 v[220:223], v176 offset:22528
	ds_read_b128 v[224:227], v176 offset:23552
	global_load_lds_dwordx4 v0, s[18:19]
	s_add_i32 m0, s40, 0x2000
	s_add_u32 s40, s18, 0x20000
	s_addc_u32 s41, s19, 0
	s_add_i32 s42, s42, s22
	global_load_lds_dwordx4 v146, s[18:19]
	s_mov_b32 m0, s42
	s_nop 0
	global_load_lds_dwordx4 v0, s[40:41]
	s_add_i32 m0, s42, 0x2000
	s_nop 0
	global_load_lds_dwordx4 v146, s[40:41]
	s_add_u32 s86, s20, s44
	s_addc_u32 s87, s21, s45
	s_mov_b32 m0, s25
	s_nop 0
	global_load_lds_dwordx4 v150, s[20:21]
	s_mov_b32 m0, s26
	s_nop 0
	global_load_lds_dwordx4 v148, s[20:21]
	s_waitcnt vmcnt(8)
	s_waitcnt lgkmcnt(0)
	s_barrier
; #define PG8_STAGE(bufoff, gbase, voff) do { _Pragma("unroll") for (int _i = 0; _i < 2; ++_i) \
;         __builtin_amdgcn_global_load_lds((const unsigned*)((const char*)(gbase) + (voff)[_i]), (PG8_LAS unsigned*)(lds + (bufoff) + ldsw + _i * 8192), 16, 0, 0); } while (0)
; #define PG8_LDA(dst, b, h) do { _Pragma("unroll") for (int m = 0; m < 4; ++m) _Pragma("unroll") for (int k = 0; k < 2; ++k) dst[m][k] = *(const PG8_LAS bf16x8*)(lds + PG8_SA(b, h) + aoff + m * 2048 + k * 1024); } while (0)
; #define PG8_LDB(dst, b, h) do { _Pragma("unroll") for (int n = 0; n < 2; ++n) _Pragma("unroll") for (int k = 0; k < 2; ++k) dst[n][k] = *(const PG8_LAS bf16x8*)(lds + PG8_SB(b, h) + boff + n * 2048 + k * 1024); } while (0)
; #define PG8_MMA(ai, bj, At, Bt) do { __builtin_amdgcn_s_setprio(1); _Pragma("unroll") for (int m = 0; m < 4; ++m) _Pragma("unroll") for (int n = 0; n < 2; ++n) _Pragma("unroll") for (int k = 0; k < 2; ++k) \
;         acc[ai][bj][m][n] = __builtin_amdgcn_mfma_f32_16x16x32_bf16(Bt[n][k], At[m][k], acc[ai][bj][m][n], 0, 0, 0); __builtin_amdgcn_s_setprio(0); } while (0)
; #define PG8_WAIT_V(n) asm volatile("s_waitcnt vmcnt(" #n ")" ::: "memory")
; #define PG8_WAIT_L(n) asm volatile("s_waitcnt lgkmcnt(" #n ")" ::: "memory")
; #define PG8_BAR __builtin_amdgcn_s_barrier()
; #define PG8_SCHED __builtin_amdgcn_sched_barrier(0)
; template <class Epi, class Sched, bool ALIGN_EPI = false, bool SP2 = false>
; __device__ __forceinline__ void gemm_phase(PG8_LAS unsigned char* lds, const Gemm g, const Sched& S, const Epi& E) {
;     ...
;             PG8_WAIT_V(8); PG8_WAIT_L(0); PG8_BAR; PG8_MMA(1, 0, At, B0); PG8_MMA(1, 1, At, B1); PG8_BAR; PG8_SCHED;
;             PG8_LDB(B0, 1, 0); PG8_LDB(B1, 1, 1); PG8_SCHED; PG8_LDA(At, 1, 0); PG8_STAGE(PG8_SA(0, 1), a2 + hstep, voffA);
;             PG8_WAIT_V(8); PG8_WAIT_L(0); PG8_BAR; PG8_MMA(0, 0, At, B0); PG8_MMA(0, 1, At, B1); PG8_BAR; PG8_SCHED;
;             PG8_LDA(At, 1, 1); PG8_STAGE(PG8_SB(1, 0), b3, voffB); PG8_STAGE(PG8_SB(1, 1), b3 + hstep, voffB); PG8_STAGE(PG8_SA(1, 0), a3, voffA);
	s_setprio 1
	s_waitcnt lgkmcnt(0)
	v_mfma_f32_16x16x32_bf16 v[62:65], v[130:133], v[182:185], 0
	v_mfma_f32_16x16x32_bf16 v[58:61], v[138:141], v[182:185], 0
	v_mfma_f32_16x16x32_bf16 v[50:53], v[130:133], v[204:207], 0
	v_mfma_f32_16x16x32_bf16 v[42:45], v[138:141], v[204:207], 0
	v_mfma_f32_16x16x32_bf16 v[34:37], v[130:133], v[212:215], 0
	v_mfma_f32_16x16x32_bf16 v[26:29], v[138:141], v[212:215], 0
	v_mfma_f32_16x16x32_bf16 v[18:21], v[130:133], v[220:223], 0
	v_mfma_f32_16x16x32_bf16 v[10:13], v[138:141], v[220:223], 0
	v_mfma_f32_16x16x32_bf16 v[62:65], v[134:137], v[200:203], v[62:65]
	v_mfma_f32_16x16x32_bf16 v[58:61], v[142:145], v[200:203], v[58:61]
	v_mfma_f32_16x16x32_bf16 v[50:53], v[134:137], v[208:211], v[50:53]
	v_mfma_f32_16x16x32_bf16 v[42:45], v[142:145], v[208:211], v[42:45]
	v_mfma_f32_16x16x32_bf16 v[34:37], v[134:137], v[216:219], v[34:37]
	v_mfma_f32_16x16x32_bf16 v[26:29], v[142:145], v[216:219], v[26:29]
	v_mfma_f32_16x16x32_bf16 v[18:21], v[134:137], v[224:227], v[18:21]
	v_mfma_f32_16x16x32_bf16 v[10:13], v[142:145], v[224:227], v[10:13]
	s_setprio 0
	s_setprio 1
	v_mfma_f32_16x16x32_bf16 v[54:57], v[156:159], v[182:185], 0
	v_mfma_f32_16x16x32_bf16 v[46:49], v[172:175], v[182:185], 0
	v_mfma_f32_16x16x32_bf16 v[38:41], v[156:159], v[204:207], 0
	v_mfma_f32_16x16x32_bf16 v[30:33], v[172:175], v[204:207], 0
	v_mfma_f32_16x16x32_bf16 v[22:25], v[156:159], v[212:215], 0
	v_mfma_f32_16x16x32_bf16 v[14:17], v[172:175], v[212:215], 0
	v_mfma_f32_16x16x32_bf16 v[6:9], v[156:159], v[220:223], 0
	v_mfma_f32_16x16x32_bf16 v[2:5], v[172:175], v[220:223], 0
	v_mfma_f32_16x16x32_bf16 v[54:57], v[164:167], v[200:203], v[54:57]
	v_mfma_f32_16x16x32_bf16 v[46:49], v[178:181], v[200:203], v[46:49]
	v_mfma_f32_16x16x32_bf16 v[38:41], v[164:167], v[208:211], v[38:41]
	v_mfma_f32_16x16x32_bf16 v[30:33], v[178:181], v[208:211], v[30:33]
	v_mfma_f32_16x16x32_bf16 v[22:25], v[164:167], v[216:219], v[22:25]
	v_mfma_f32_16x16x32_bf16 v[14:17], v[178:181], v[216:219], v[14:17]
	v_mfma_f32_16x16x32_bf16 v[6:9], v[164:167], v[224:227], v[6:9]
	v_mfma_f32_16x16x32_bf16 v[2:5], v[178:181], v[224:227], v[2:5]
	s_setprio 0
	s_barrier
	s_add_i32 s40, 0, 0x18000
	s_add_i32 s41, 0, 0x1c000
	v_add_u32_e32 v142, s40, v161
	v_add_u32_e32 v177, s41, v161
	ds_read_b128 v[130:133], v142
	ds_read_b128 v[134:137], v142 offset:1024
	ds_read_b128 v[138:141], v142 offset:2048
	ds_read_b128 v[142:145], v142 offset:3072
	ds_read_b128 v[156:159], v177
	ds_read_b128 v[164:167], v177 offset:1024
	ds_read_b128 v[172:175], v177 offset:2048
	ds_read_b128 v[178:181], v177 offset:3072
	s_add_u32 s20, s20, 0x20000
	s_addc_u32 s21, s21, 0
	s_mov_b32 m0, s27
	ds_read_b128 v[182:185], v176 offset:32768
	ds_read_b128 v[200:203], v176 offset:33792
	ds_read_b128 v[204:207], v176 offset:34816
	ds_read_b128 v[208:211], v176 offset:35840
	ds_read_b128 v[212:215], v176 offset:36864
	ds_read_b128 v[216:219], v176 offset:37888
	ds_read_b128 v[220:223], v176 offset:38912
	ds_read_b128 v[224:227], v176 offset:39936
	global_load_lds_dwordx4 v150, s[20:21]
	s_mov_b32 m0, s28
	s_nop 0
	global_load_lds_dwordx4 v148, s[20:21]
	s_waitcnt vmcnt(8)
	s_waitcnt lgkmcnt(0)
	s_barrier
	s_setprio 1
	s_waitcnt lgkmcnt(0)
	v_mfma_f32_16x16x32_bf16 v[126:129], v[130:133], v[182:185], v[126:129]
	v_mfma_f32_16x16x32_bf16 v[122:125], v[138:141], v[182:185], v[122:125]
	v_mfma_f32_16x16x32_bf16 v[114:117], v[130:133], v[204:207], v[114:117]
	v_mfma_f32_16x16x32_bf16 v[106:109], v[138:141], v[204:207], v[106:109]
	v_mfma_f32_16x16x32_bf16 v[98:101], v[130:133], v[212:215], v[98:101]
	v_mfma_f32_16x16x32_bf16 v[90:93], v[138:141], v[212:215], v[90:93]
	v_mfma_f32_16x16x32_bf16 v[82:85], v[130:133], v[220:223], v[82:85]
	v_mfma_f32_16x16x32_bf16 v[74:77], v[138:141], v[220:223], v[74:77]
	v_mfma_f32_16x16x32_bf16 v[126:129], v[134:137], v[200:203], v[126:129]
	v_mfma_f32_16x16x32_bf16 v[122:125], v[142:145], v[200:203], v[122:125]
	v_mfma_f32_16x16x32_bf16 v[114:117], v[134:137], v[208:211], v[114:117]
	v_mfma_f32_16x16x32_bf16 v[106:109], v[142:145], v[208:211], v[106:109]
	v_mfma_f32_16x16x32_bf16 v[98:101], v[134:137], v[216:219], v[98:101]
	v_mfma_f32_16x16x32_bf16 v[90:93], v[142:145], v[216:219], v[90:93]
	v_mfma_f32_16x16x32_bf16 v[82:85], v[134:137], v[224:227], v[82:85]
	v_mfma_f32_16x16x32_bf16 v[74:77], v[142:145], v[224:227], v[74:77]
	s_setprio 0
	s_setprio 1
	v_mfma_f32_16x16x32_bf16 v[118:121], v[156:159], v[182:185], v[118:121]
	v_mfma_f32_16x16x32_bf16 v[110:113], v[172:175], v[182:185], v[110:113]
	v_mfma_f32_16x16x32_bf16 v[102:105], v[156:159], v[204:207], v[102:105]
	v_mfma_f32_16x16x32_bf16 v[94:97], v[172:175], v[204:207], v[94:97]
	v_mfma_f32_16x16x32_bf16 v[86:89], v[156:159], v[212:215], v[86:89]
	v_mfma_f32_16x16x32_bf16 v[78:81], v[172:175], v[212:215], v[78:81]
	v_mfma_f32_16x16x32_bf16 v[70:73], v[156:159], v[220:223], v[70:73]
	v_mfma_f32_16x16x32_bf16 v[66:69], v[172:175], v[220:223], v[66:69]
	v_mfma_f32_16x16x32_bf16 v[118:121], v[164:167], v[200:203], v[118:121]
	v_mfma_f32_16x16x32_bf16 v[110:113], v[178:181], v[200:203], v[110:113]
	v_mfma_f32_16x16x32_bf16 v[102:105], v[164:167], v[208:211], v[102:105]
	v_mfma_f32_16x16x32_bf16 v[94:97], v[178:181], v[208:211], v[94:97]
	v_mfma_f32_16x16x32_bf16 v[86:89], v[164:167], v[216:219], v[86:89]
	v_mfma_f32_16x16x32_bf16 v[78:81], v[178:181], v[216:219], v[78:81]
	v_mfma_f32_16x16x32_bf16 v[70:73], v[164:167], v[224:227], v[70:73]
	v_mfma_f32_16x16x32_bf16 v[66:69], v[178:181], v[224:227], v[66:69]
	s_setprio 0
	s_barrier
; #define PG8_STAGE(bufoff, gbase, voff) do { _Pragma("unroll") for (int _i = 0; _i < 2; ++_i) \
;         __builtin_amdgcn_global_load_lds((const unsigned*)((const char*)(gbase) + (voff)[_i]), (PG8_LAS unsigned*)(lds + (bufoff) + ldsw + _i * 8192), 16, 0, 0); } while (0)
; #define PG8_LDA(dst, b, h) do { _Pragma("unroll") for (int m = 0; m < 4; ++m) _Pragma("unroll") for (int k = 0; k < 2; ++k) dst[m][k] = *(const PG8_LAS bf16x8*)(lds + PG8_SA(b, h) + aoff + m * 2048 + k * 1024); } while (0)
; #define PG8_LDB(dst, b, h) do { _Pragma("unroll") for (int n = 0; n < 2; ++n) _Pragma("unroll") for (int k = 0; k < 2; ++k) dst[n][k] = *(const PG8_LAS bf16x8*)(lds + PG8_SB(b, h) + boff + n * 2048 + k * 1024); } while (0)
; #define PG8_WAIT_V(n) asm volatile("s_waitcnt vmcnt(" #n ")" ::: "memory")
; #define PG8_WAIT_L(n) asm volatile("s_waitcnt lgkmcnt(" #n ")" ::: "memory")
; #define PG8_BAR __builtin_amdgcn_s_barrier()
; template <class Epi, class Sched, bool ALIGN_EPI = false, bool SP2 = false>
; __device__ __forceinline__ void gemm_phase(PG8_LAS unsigned char* lds, const Gemm g, const Sched& S, const Epi& E) {
;     ...
;         for (int t = 0; t < nt; t += 2) {
;             const bool last = (t == nt - 2);
;             const char* a1 = cA + (size_t)(t + 1) * kstep;
;             const char* a2 = last ? nA : cA + (size_t)(t + 2) * kstep; const char* b2 = last ? nB : cB + (size_t)(t + 2) * kstep;
;             const char* a3 = a2 + kstep; const char* b3 = b2 + kstep;
;             if (last && has_next) S.a_ready(nxt);
;             if constexpr (SP2) {
;             PG8_LDB(B0, 0, 0); PG8_LDB(B1, 0, 1); PG8_SCHED; PG8_LDA(At, 0, 0); PG8_STAGE(PG8_SA(1, 1), a1 + hstep, voffA);
;             PG8_WAIT_V(8); PG8_WAIT_L(0); PG8_BAR; PG8_MMA(0, 0, At, B0); PG8_MMA(0, 1, At, B1); PG8_BAR; PG8_SCHED;
;             PG8_LDA(At, 0, 1); PG8_STAGE(PG8_SB(0, 0), b2, voffB); PG8_STAGE(PG8_SB(0, 1), b2 + hstep, voffB); PG8_STAGE(PG8_SA(0, 0), a2, voffA);
;             PG8_WAIT_V(8); PG8_WAIT_L(0); PG8_BAR; PG8_MMA(1, 0, At, B0); PG8_MMA(1, 1, At, B1); PG8_BAR; PG8_SCHED;
;     ...
;             PG8_LDA(At, 1, 1); PG8_STAGE(PG8_SB(1, 0), b3, voffB); PG8_STAGE(PG8_SB(1, 1), b3 + hstep, voffB); PG8_STAGE(PG8_SA(1, 0), a3, voffA);
;             PG8_WAIT_V(8); PG8_WAIT_L(0); PG8_BAR; PG8_MMA(1, 0, At, B0); PG8_MMA(1, 1, At, B1); PG8_BAR; PG8_SCHED;
	s_add_i32 s20, s40, s22
	s_mov_b32 m0, s20
	ds_read_b128 v[182:185], v176 offset:49152
	ds_read_b128 v[200:203], v176 offset:50176
	ds_read_b128 v[204:207], v176 offset:51200
	ds_read_b128 v[208:211], v176 offset:52224
	ds_read_b128 v[212:215], v176 offset:53248
	ds_read_b128 v[216:219], v176 offset:54272
	ds_read_b128 v[220:223], v176 offset:55296
	ds_read_b128 v[224:227], v176 offset:56320
	global_load_lds_dwordx4 v0, s[84:85]
	s_add_i32 m0, s20, 0x2000
	s_add_u32 s18, s18, 0x20080
	s_addc_u32 s19, s19, 0
	s_add_i32 s20, s41, s22
	global_load_lds_dwordx4 v146, s[84:85]
	s_mov_b32 m0, s20
	s_nop 0
	global_load_lds_dwordx4 v0, s[18:19]
	s_add_i32 m0, s20, 0x2000
	s_nop 0
	global_load_lds_dwordx4 v146, s[18:19]
	s_mov_b32 m0, s29
	s_nop 0
	global_load_lds_dwordx4 v150, s[86:87]
	s_mov_b32 m0, s30
	s_nop 0
	global_load_lds_dwordx4 v148, s[86:87]
	s_waitcnt vmcnt(8)
	s_waitcnt lgkmcnt(0)
	s_barrier
	s_setprio 1
	s_waitcnt lgkmcnt(0)
	v_mfma_f32_16x16x32_bf16 v[62:65], v[130:133], v[182:185], v[62:65]
	v_mfma_f32_16x16x32_bf16 v[58:61], v[138:141], v[182:185], v[58:61]
	v_mfma_f32_16x16x32_bf16 v[50:53], v[130:133], v[204:207], v[50:53]
	v_mfma_f32_16x16x32_bf16 v[42:45], v[138:141], v[204:207], v[42:45]
	v_mfma_f32_16x16x32_bf16 v[34:37], v[130:133], v[212:215], v[34:37]
	v_mfma_f32_16x16x32_bf16 v[26:29], v[138:141], v[212:215], v[26:29]
	v_mfma_f32_16x16x32_bf16 v[18:21], v[130:133], v[220:223], v[18:21]
	v_mfma_f32_16x16x32_bf16 v[10:13], v[138:141], v[220:223], v[10:13]
	v_mfma_f32_16x16x32_bf16 v[62:65], v[134:137], v[200:203], v[62:65]
	v_mfma_f32_16x16x32_bf16 v[58:61], v[142:145], v[200:203], v[58:61]
	v_mfma_f32_16x16x32_bf16 v[50:53], v[134:137], v[208:211], v[50:53]
	v_mfma_f32_16x16x32_bf16 v[42:45], v[142:145], v[208:211], v[42:45]
	v_mfma_f32_16x16x32_bf16 v[34:37], v[134:137], v[216:219], v[34:37]
	v_mfma_f32_16x16x32_bf16 v[26:29], v[142:145], v[216:219], v[26:29]
	v_mfma_f32_16x16x32_bf16 v[18:21], v[134:137], v[224:227], v[18:21]
	v_mfma_f32_16x16x32_bf16 v[10:13], v[142:145], v[224:227], v[10:13]
	s_setprio 0
	s_setprio 1
	v_mfma_f32_16x16x32_bf16 v[54:57], v[156:159], v[182:185], v[54:57]
	v_mfma_f32_16x16x32_bf16 v[46:49], v[172:175], v[182:185], v[46:49]
	v_mfma_f32_16x16x32_bf16 v[38:41], v[156:159], v[204:207], v[38:41]
	v_mfma_f32_16x16x32_bf16 v[30:33], v[172:175], v[204:207], v[30:33]
	v_mfma_f32_16x16x32_bf16 v[22:25], v[156:159], v[212:215], v[22:25]
	v_mfma_f32_16x16x32_bf16 v[14:17], v[172:175], v[212:215], v[14:17]
	v_mfma_f32_16x16x32_bf16 v[6:9], v[156:159], v[220:223], v[6:9]
	v_mfma_f32_16x16x32_bf16 v[2:5], v[172:175], v[220:223], v[2:5]
	v_mfma_f32_16x16x32_bf16 v[54:57], v[164:167], v[200:203], v[54:57]
	v_mfma_f32_16x16x32_bf16 v[46:49], v[178:181], v[200:203], v[46:49]
	v_mfma_f32_16x16x32_bf16 v[38:41], v[164:167], v[208:211], v[38:41]
	v_mfma_f32_16x16x32_bf16 v[30:33], v[178:181], v[208:211], v[30:33]
	v_mfma_f32_16x16x32_bf16 v[22:25], v[164:167], v[216:219], v[22:25]
	v_mfma_f32_16x16x32_bf16 v[14:17], v[178:181], v[216:219], v[14:17]
	v_mfma_f32_16x16x32_bf16 v[6:9], v[164:167], v[224:227], v[6:9]
	v_mfma_f32_16x16x32_bf16 v[2:5], v[178:181], v[224:227], v[2:5]
	s_setprio 0
	s_barrier
	s_add_i32 s39, s39, 2
	s_add_u32 s0, s0, 0x100
	s_addc_u32 s1, s1, 0
	s_add_u32 s37, s37, 0x100
	s_addc_u32 s38, s38, 0
	s_cmp_gt_u32 s39, 5
.LBB0_745:
	s_add_u32 s18, s0, 0xfffe0080
	s_addc_u32 s19, s1, -1
	s_add_i32 s40, 0, 0x10000
	s_cmp_eq_u32 s39, 4
	s_cselect_b32 s21, s9, s19
	s_cselect_b32 s20, s35, s18
	s_cselect_b32 s19, s11, s38
	s_cselect_b32 s18, s36, s37
	s_add_i32 s42, 0, 0x14000
	v_add_u32_e32 v142, s40, v161
	v_add_u32_e32 v177, s42, v161
	ds_read_b128 v[130:133], v142
	ds_read_b128 v[134:137], v142 offset:1024
	ds_read_b128 v[138:141], v142 offset:2048
	ds_read_b128 v[142:145], v142 offset:3072
	ds_read_b128 v[156:159], v177
	ds_read_b128 v[164:167], v177 offset:1024
	ds_read_b128 v[172:175], v177 offset:2048
	ds_read_b128 v[178:181], v177 offset:3072
	s_add_i32 m0, s25, 0xc000
	ds_read_b128 v[182:185], v176
	ds_read_b128 v[200:203], v176 offset:1024
	ds_read_b128 v[204:207], v176 offset:2048
	ds_read_b128 v[208:211], v176 offset:3072
	ds_read_b128 v[212:215], v176 offset:4096
	ds_read_b128 v[216:219], v176 offset:5120
	ds_read_b128 v[220:223], v176 offset:6144
	ds_read_b128 v[224:227], v176 offset:7168
	global_load_lds_dwordx4 v152, s[0:1]
	s_add_i32 m0, s25, 0xe000
	s_nop 0
	global_load_lds_dwordx4 v154, s[0:1]
	s_waitcnt vmcnt(8)
	s_waitcnt lgkmcnt(0)
	s_barrier
; #define PG8_STAGE(bufoff, gbase, voff) do { _Pragma("unroll") for (int _i = 0; _i < 2; ++_i) \
;         __builtin_amdgcn_global_load_lds((const unsigned*)((const char*)(gbase) + (voff)[_i]), (PG8_LAS unsigned*)(lds + (bufoff) + ldsw + _i * 8192), 16, 0, 0); } while (0)
; #define PG8_LDA(dst, b, h) do { _Pragma("unroll") for (int m = 0; m < 4; ++m) _Pragma("unroll") for (int k = 0; k < 2; ++k) dst[m][k] = *(const PG8_LAS bf16x8*)(lds + PG8_SA(b, h) + aoff + m * 2048 + k * 1024); } while (0)
; #define PG8_MMA(ai, bj, At, Bt) do { __builtin_amdgcn_s_setprio(1); _Pragma("unroll") for (int m = 0; m < 4; ++m) _Pragma("unroll") for (int n = 0; n < 2; ++n) _Pragma("unroll") for (int k = 0; k < 2; ++k) \
;         acc[ai][bj][m][n] = __builtin_amdgcn_mfma_f32_16x16x32_bf16(Bt[n][k], At[m][k], acc[ai][bj][m][n], 0, 0, 0); __builtin_amdgcn_s_setprio(0); } while (0)
; #define PG8_WAIT_V(n) asm volatile("s_waitcnt vmcnt(" #n ")" ::: "memory")
; #define PG8_WAIT_L(n) asm volatile("s_waitcnt lgkmcnt(" #n ")" ::: "memory")
; #define PG8_BAR __builtin_amdgcn_s_barrier()
; #define PG8_SCHED __builtin_amdgcn_sched_barrier(0)
; template <class Epi, class Sched, bool ALIGN_EPI = false, bool SP2 = false>
; __device__ __forceinline__ void gemm_phase(PG8_LAS unsigned char* lds, const Gemm g, const Sched& S, const Epi& E) {
;     ...
;             PG8_WAIT_V(8); PG8_WAIT_L(0); PG8_BAR; PG8_MMA(0, 0, At, B0); PG8_MMA(0, 1, At, B1); PG8_BAR; PG8_SCHED;
;             PG8_LDA(At, 0, 1); PG8_STAGE(PG8_SB(0, 0), b2, voffB); PG8_STAGE(PG8_SB(0, 1), b2 + hstep, voffB); PG8_STAGE(PG8_SA(0, 0), a2, voffA);
;             PG8_WAIT_V(8); PG8_WAIT_L(0); PG8_BAR; PG8_MMA(1, 0, At, B0); PG8_MMA(1, 1, At, B1); PG8_BAR; PG8_SCHED;
	s_setprio 1
	s_waitcnt lgkmcnt(0)
	v_mfma_f32_16x16x32_bf16 v[126:129], v[130:133], v[182:185], v[126:129]
	v_mfma_f32_16x16x32_bf16 v[122:125], v[138:141], v[182:185], v[122:125]
	v_mfma_f32_16x16x32_bf16 v[114:117], v[130:133], v[204:207], v[114:117]
	v_mfma_f32_16x16x32_bf16 v[106:109], v[138:141], v[204:207], v[106:109]
	v_mfma_f32_16x16x32_bf16 v[98:101], v[130:133], v[212:215], v[98:101]
	v_mfma_f32_16x16x32_bf16 v[90:93], v[138:141], v[212:215], v[90:93]
	v_mfma_f32_16x16x32_bf16 v[82:85], v[130:133], v[220:223], v[82:85]
	v_mfma_f32_16x16x32_bf16 v[74:77], v[138:141], v[220:223], v[74:77]
	v_mfma_f32_16x16x32_bf16 v[126:129], v[134:137], v[200:203], v[126:129]
	v_mfma_f32_16x16x32_bf16 v[122:125], v[142:145], v[200:203], v[122:125]
	v_mfma_f32_16x16x32_bf16 v[114:117], v[134:137], v[208:211], v[114:117]
	v_mfma_f32_16x16x32_bf16 v[106:109], v[142:145], v[208:211], v[106:109]
	v_mfma_f32_16x16x32_bf16 v[98:101], v[134:137], v[216:219], v[98:101]
	v_mfma_f32_16x16x32_bf16 v[90:93], v[142:145], v[216:219], v[90:93]
	v_mfma_f32_16x16x32_bf16 v[82:85], v[134:137], v[224:227], v[82:85]
	v_mfma_f32_16x16x32_bf16 v[74:77], v[142:145], v[224:227], v[74:77]
	s_setprio 0
	s_setprio 1
	v_mfma_f32_16x16x32_bf16 v[118:121], v[156:159], v[182:185], v[118:121]
	v_mfma_f32_16x16x32_bf16 v[110:113], v[172:175], v[182:185], v[110:113]
	v_mfma_f32_16x16x32_bf16 v[102:105], v[156:159], v[204:207], v[102:105]
	v_mfma_f32_16x16x32_bf16 v[94:97], v[172:175], v[204:207], v[94:97]
	v_mfma_f32_16x16x32_bf16 v[86:89], v[156:159], v[212:215], v[86:89]
	v_mfma_f32_16x16x32_bf16 v[78:81], v[172:175], v[212:215], v[78:81]
	v_mfma_f32_16x16x32_bf16 v[70:73], v[156:159], v[220:223], v[70:73]
	v_mfma_f32_16x16x32_bf16 v[66:69], v[172:175], v[220:223], v[66:69]
	v_mfma_f32_16x16x32_bf16 v[118:121], v[164:167], v[200:203], v[118:121]
	v_mfma_f32_16x16x32_bf16 v[110:113], v[178:181], v[200:203], v[110:113]
	v_mfma_f32_16x16x32_bf16 v[102:105], v[164:167], v[208:211], v[102:105]
	v_mfma_f32_16x16x32_bf16 v[94:97], v[178:181], v[208:211], v[94:97]
	v_mfma_f32_16x16x32_bf16 v[86:89], v[164:167], v[216:219], v[86:89]
	v_mfma_f32_16x16x32_bf16 v[78:81], v[178:181], v[216:219], v[78:81]
	v_mfma_f32_16x16x32_bf16 v[70:73], v[164:167], v[224:227], v[70:73]
	v_mfma_f32_16x16x32_bf16 v[66:69], v[178:181], v[224:227], v[66:69]
	s_setprio 0
	s_barrier
	s_add_i32 s40, s40, s22
	s_add_u32 s84, s18, s44
	s_addc_u32 s85, s19, s45
	s_mov_b32 m0, s40
	ds_read_b128 v[182:185], v176 offset:16384
	ds_read_b128 v[200:203], v176 offset:17408
	ds_read_b128 v[204:207], v176 offset:18432
	ds_read_b128 v[208:211], v176 offset:19456
	ds_read_b128 v[212:215], v176 offset:20480
	ds_read_b128 v[216:219], v176 offset:21504
	ds_read_b128 v[220:223], v176 offset:22528
	ds_read_b128 v[224:227], v176 offset:23552
	global_load_lds_dwordx4 v0, s[18:19]
	s_add_i32 m0, s40, 0x2000
	s_add_u32 s40, s18, 0x20000
	s_addc_u32 s41, s19, 0
	s_add_i32 s42, s42, s22
	global_load_lds_dwordx4 v146, s[18:19]
	s_mov_b32 m0, s42
	s_nop 0
	global_load_lds_dwordx4 v0, s[40:41]
	s_add_i32 m0, s42, 0x2000
	s_nop 0
	global_load_lds_dwordx4 v146, s[40:41]
	s_add_u32 s86, s20, s44
	s_addc_u32 s87, s21, s45
	s_mov_b32 m0, s25
	s_nop 0
	global_load_lds_dwordx4 v150, s[20:21]
	s_mov_b32 m0, s26
	s_nop 0
	global_load_lds_dwordx4 v148, s[20:21]
	s_waitcnt vmcnt(8)
	s_waitcnt lgkmcnt(0)
	s_barrier
	s_setprio 1
	s_waitcnt lgkmcnt(0)
	v_mfma_f32_16x16x32_bf16 v[62:65], v[130:133], v[182:185], v[62:65]
	v_mfma_f32_16x16x32_bf16 v[58:61], v[138:141], v[182:185], v[58:61]
	v_mfma_f32_16x16x32_bf16 v[50:53], v[130:133], v[204:207], v[50:53]
	v_mfma_f32_16x16x32_bf16 v[42:45], v[138:141], v[204:207], v[42:45]
	v_mfma_f32_16x16x32_bf16 v[34:37], v[130:133], v[212:215], v[34:37]
	v_mfma_f32_16x16x32_bf16 v[26:29], v[138:141], v[212:215], v[26:29]
	v_mfma_f32_16x16x32_bf16 v[18:21], v[130:133], v[220:223], v[18:21]
	v_mfma_f32_16x16x32_bf16 v[10:13], v[138:141], v[220:223], v[10:13]
	v_mfma_f32_16x16x32_bf16 v[62:65], v[134:137], v[200:203], v[62:65]
	v_mfma_f32_16x16x32_bf16 v[58:61], v[142:145], v[200:203], v[58:61]
	v_mfma_f32_16x16x32_bf16 v[50:53], v[134:137], v[208:211], v[50:53]
	v_mfma_f32_16x16x32_bf16 v[42:45], v[142:145], v[208:211], v[42:45]
	v_mfma_f32_16x16x32_bf16 v[34:37], v[134:137], v[216:219], v[34:37]
	v_mfma_f32_16x16x32_bf16 v[26:29], v[142:145], v[216:219], v[26:29]
	v_mfma_f32_16x16x32_bf16 v[18:21], v[134:137], v[224:227], v[18:21]
	v_mfma_f32_16x16x32_bf16 v[10:13], v[142:145], v[224:227], v[10:13]
	s_setprio 0
	s_setprio 1
	v_mfma_f32_16x16x32_bf16 v[54:57], v[156:159], v[182:185], v[54:57]
	v_mfma_f32_16x16x32_bf16 v[46:49], v[172:175], v[182:185], v[46:49]
	v_mfma_f32_16x16x32_bf16 v[38:41], v[156:159], v[204:207], v[38:41]
	v_mfma_f32_16x16x32_bf16 v[30:33], v[172:175], v[204:207], v[30:33]
	v_mfma_f32_16x16x32_bf16 v[22:25], v[156:159], v[212:215], v[22:25]
	v_mfma_f32_16x16x32_bf16 v[14:17], v[172:175], v[212:215], v[14:17]
	v_mfma_f32_16x16x32_bf16 v[6:9], v[156:159], v[220:223], v[6:9]
	v_mfma_f32_16x16x32_bf16 v[2:5], v[172:175], v[220:223], v[2:5]
	v_mfma_f32_16x16x32_bf16 v[54:57], v[164:167], v[200:203], v[54:57]
	v_mfma_f32_16x16x32_bf16 v[46:49], v[178:181], v[200:203], v[46:49]
	v_mfma_f32_16x16x32_bf16 v[38:41], v[164:167], v[208:211], v[38:41]
	v_mfma_f32_16x16x32_bf16 v[30:33], v[178:181], v[208:211], v[30:33]
	v_mfma_f32_16x16x32_bf16 v[22:25], v[164:167], v[216:219], v[22:25]
	v_mfma_f32_16x16x32_bf16 v[14:17], v[178:181], v[216:219], v[14:17]
	v_mfma_f32_16x16x32_bf16 v[6:9], v[164:167], v[224:227], v[6:9]
	v_mfma_f32_16x16x32_bf16 v[2:5], v[178:181], v[224:227], v[2:5]
	s_setprio 0
	s_barrier
; #define PG8_STAGE(bufoff, gbase, voff) do { _Pragma("unroll") for (int _i = 0; _i < 2; ++_i) \
;         __builtin_amdgcn_global_load_lds((const unsigned*)((const char*)(gbase) + (voff)[_i]), (PG8_LAS unsigned*)(lds + (bufoff) + ldsw + _i * 8192), 16, 0, 0); } while (0)
; #define PG8_LDA(dst, b, h) do { _Pragma("unroll") for (int m = 0; m < 4; ++m) _Pragma("unroll") for (int k = 0; k < 2; ++k) dst[m][k] = *(const PG8_LAS bf16x8*)(lds + PG8_SA(b, h) + aoff + m * 2048 + k * 1024); } while (0)
; #define PG8_LDB(dst, b, h) do { _Pragma("unroll") for (int n = 0; n < 2; ++n) _Pragma("unroll") for (int k = 0; k < 2; ++k) dst[n][k] = *(const PG8_LAS bf16x8*)(lds + PG8_SB(b, h) + boff + n * 2048 + k * 1024); } while (0)
; #define PG8_MMA(ai, bj, At, Bt) do { __builtin_amdgcn_s_setprio(1); _Pragma("unroll") for (int m = 0; m < 4; ++m) _Pragma("unroll") for (int n = 0; n < 2; ++n) _Pragma("unroll") for (int k = 0; k < 2; ++k) \
;         acc[ai][bj][m][n] = __builtin_amdgcn_mfma_f32_16x16x32_bf16(Bt[n][k], At[m][k], acc[ai][bj][m][n], 0, 0, 0); __builtin_amdgcn_s_setprio(0); } while (0)
; #define PG8_WAIT_V(n) asm volatile("s_waitcnt vmcnt(" #n ")" ::: "memory")
; #define PG8_WAIT_L(n) asm volatile("s_waitcnt lgkmcnt(" #n ")" ::: "memory")
; #define PG8_BAR __builtin_amdgcn_s_barrier()
; template <class Epi, class Sched, bool ALIGN_EPI = false, bool SP2 = false>
; __device__ __forceinline__ void gemm_phase(PG8_LAS unsigned char* lds, const Gemm g, const Sched& S, const Epi& E) {
;     ...
;         for (int t = 0; t < nt; t += 2) {
;             const bool last = (t == nt - 2);
;             const char* a1 = cA + (size_t)(t + 1) * kstep;
;             const char* a2 = last ? nA : cA + (size_t)(t + 2) * kstep; const char* b2 = last ? nB : cB + (size_t)(t + 2) * kstep;
;             const char* a3 = a2 + kstep; const char* b3 = b2 + kstep;
;     ...
;             PG8_LDB(B0, 1, 0); PG8_LDB(B1, 1, 1); PG8_SCHED; PG8_LDA(At, 1, 0); PG8_STAGE(PG8_SA(0, 1), a2 + hstep, voffA);
;             PG8_WAIT_V(8); PG8_WAIT_L(0); PG8_BAR; PG8_MMA(0, 0, At, B0); PG8_MMA(0, 1, At, B1); PG8_BAR; PG8_SCHED;
;             PG8_LDA(At, 1, 1); PG8_STAGE(PG8_SB(1, 0), b3, voffB); PG8_STAGE(PG8_SB(1, 1), b3 + hstep, voffB); PG8_STAGE(PG8_SA(1, 0), a3, voffA);
;             PG8_WAIT_V(8); PG8_WAIT_L(0); PG8_BAR; PG8_MMA(1, 0, At, B0); PG8_MMA(1, 1, At, B1); PG8_BAR; PG8_SCHED;
	s_add_i32 s40, 0, 0x18000
	s_add_i32 s41, 0, 0x1c000
	v_add_u32_e32 v142, s40, v161
	v_add_u32_e32 v177, s41, v161
	ds_read_b128 v[130:133], v142
	ds_read_b128 v[134:137], v142 offset:1024
	ds_read_b128 v[138:141], v142 offset:2048
	ds_read_b128 v[142:145], v142 offset:3072
	ds_read_b128 v[156:159], v177
	ds_read_b128 v[164:167], v177 offset:1024
	ds_read_b128 v[172:175], v177 offset:2048
	ds_read_b128 v[178:181], v177 offset:3072
	s_add_u32 s20, s20, 0x20000
	s_addc_u32 s21, s21, 0
	s_mov_b32 m0, s27
	ds_read_b128 v[182:185], v176 offset:32768
	ds_read_b128 v[200:203], v176 offset:33792
	ds_read_b128 v[204:207], v176 offset:34816
	ds_read_b128 v[208:211], v176 offset:35840
	ds_read_b128 v[212:215], v176 offset:36864
	ds_read_b128 v[216:219], v176 offset:37888
	ds_read_b128 v[220:223], v176 offset:38912
	ds_read_b128 v[224:227], v176 offset:39936
	global_load_lds_dwordx4 v150, s[20:21]
	s_mov_b32 m0, s28
	s_nop 0
	global_load_lds_dwordx4 v148, s[20:21]
	s_waitcnt vmcnt(8)
	s_waitcnt lgkmcnt(0)
	s_barrier
	s_setprio 1
	s_waitcnt lgkmcnt(0)
	v_mfma_f32_16x16x32_bf16 v[126:129], v[130:133], v[182:185], v[126:129]
	v_mfma_f32_16x16x32_bf16 v[122:125], v[138:141], v[182:185], v[122:125]
	v_mfma_f32_16x16x32_bf16 v[114:117], v[130:133], v[204:207], v[114:117]
	v_mfma_f32_16x16x32_bf16 v[106:109], v[138:141], v[204:207], v[106:109]
	v_mfma_f32_16x16x32_bf16 v[98:101], v[130:133], v[212:215], v[98:101]
	v_mfma_f32_16x16x32_bf16 v[90:93], v[138:141], v[212:215], v[90:93]
	v_mfma_f32_16x16x32_bf16 v[82:85], v[130:133], v[220:223], v[82:85]
	v_mfma_f32_16x16x32_bf16 v[74:77], v[138:141], v[220:223], v[74:77]
	v_mfma_f32_16x16x32_bf16 v[126:129], v[134:137], v[200:203], v[126:129]
	v_mfma_f32_16x16x32_bf16 v[122:125], v[142:145], v[200:203], v[122:125]
	v_mfma_f32_16x16x32_bf16 v[114:117], v[134:137], v[208:211], v[114:117]
	v_mfma_f32_16x16x32_bf16 v[106:109], v[142:145], v[208:211], v[106:109]
	v_mfma_f32_16x16x32_bf16 v[98:101], v[134:137], v[216:219], v[98:101]
	v_mfma_f32_16x16x32_bf16 v[90:93], v[142:145], v[216:219], v[90:93]
	v_mfma_f32_16x16x32_bf16 v[82:85], v[134:137], v[224:227], v[82:85]
	v_mfma_f32_16x16x32_bf16 v[74:77], v[142:145], v[224:227], v[74:77]
	s_setprio 0
	s_setprio 1
	v_mfma_f32_16x16x32_bf16 v[118:121], v[156:159], v[182:185], v[118:121]
	v_mfma_f32_16x16x32_bf16 v[110:113], v[172:175], v[182:185], v[110:113]
	v_mfma_f32_16x16x32_bf16 v[102:105], v[156:159], v[204:207], v[102:105]
	v_mfma_f32_16x16x32_bf16 v[94:97], v[172:175], v[204:207], v[94:97]
	v_mfma_f32_16x16x32_bf16 v[86:89], v[156:159], v[212:215], v[86:89]
	v_mfma_f32_16x16x32_bf16 v[78:81], v[172:175], v[212:215], v[78:81]
	v_mfma_f32_16x16x32_bf16 v[70:73], v[156:159], v[220:223], v[70:73]
	v_mfma_f32_16x16x32_bf16 v[66:69], v[172:175], v[220:223], v[66:69]
	v_mfma_f32_16x16x32_bf16 v[118:121], v[164:167], v[200:203], v[118:121]
	v_mfma_f32_16x16x32_bf16 v[110:113], v[178:181], v[200:203], v[110:113]
	v_mfma_f32_16x16x32_bf16 v[102:105], v[164:167], v[208:211], v[102:105]
	v_mfma_f32_16x16x32_bf16 v[94:97], v[178:181], v[208:211], v[94:97]
	v_mfma_f32_16x16x32_bf16 v[86:89], v[164:167], v[216:219], v[86:89]
	v_mfma_f32_16x16x32_bf16 v[78:81], v[178:181], v[216:219], v[78:81]
	v_mfma_f32_16x16x32_bf16 v[70:73], v[164:167], v[224:227], v[70:73]
	v_mfma_f32_16x16x32_bf16 v[66:69], v[178:181], v[224:227], v[66:69]
	s_setprio 0
	s_barrier
	s_add_i32 s20, s40, s22
	s_mov_b32 m0, s20
	ds_read_b128 v[182:185], v176 offset:49152
	ds_read_b128 v[200:203], v176 offset:50176
	ds_read_b128 v[204:207], v176 offset:51200
	ds_read_b128 v[208:211], v176 offset:52224
	ds_read_b128 v[212:215], v176 offset:53248
	ds_read_b128 v[216:219], v176 offset:54272
	ds_read_b128 v[220:223], v176 offset:55296
	ds_read_b128 v[224:227], v176 offset:56320
	global_load_lds_dwordx4 v0, s[84:85]
	s_add_i32 m0, s20, 0x2000
	s_add_u32 s18, s18, 0x20080
	s_addc_u32 s19, s19, 0
	s_add_i32 s20, s41, s22
	global_load_lds_dwordx4 v146, s[84:85]
	s_mov_b32 m0, s20
	s_nop 0
	global_load_lds_dwordx4 v0, s[18:19]
	s_add_i32 m0, s20, 0x2000
	s_nop 0
	global_load_lds_dwordx4 v146, s[18:19]
	s_mov_b32 m0, s29
	s_nop 0
	global_load_lds_dwordx4 v150, s[86:87]
	s_mov_b32 m0, s30
	s_nop 0
	global_load_lds_dwordx4 v148, s[86:87]
	s_waitcnt vmcnt(8)
	s_waitcnt lgkmcnt(0)
	s_barrier
	s_setprio 1
	s_waitcnt lgkmcnt(0)
	v_mfma_f32_16x16x32_bf16 v[62:65], v[130:133], v[182:185], v[62:65]
	v_mfma_f32_16x16x32_bf16 v[58:61], v[138:141], v[182:185], v[58:61]
	v_mfma_f32_16x16x32_bf16 v[50:53], v[130:133], v[204:207], v[50:53]
	v_mfma_f32_16x16x32_bf16 v[42:45], v[138:141], v[204:207], v[42:45]
	v_mfma_f32_16x16x32_bf16 v[34:37], v[130:133], v[212:215], v[34:37]
	v_mfma_f32_16x16x32_bf16 v[26:29], v[138:141], v[212:215], v[26:29]
	v_mfma_f32_16x16x32_bf16 v[18:21], v[130:133], v[220:223], v[18:21]
	v_mfma_f32_16x16x32_bf16 v[10:13], v[138:141], v[220:223], v[10:13]
	v_mfma_f32_16x16x32_bf16 v[62:65], v[134:137], v[200:203], v[62:65]
	v_mfma_f32_16x16x32_bf16 v[58:61], v[142:145], v[200:203], v[58:61]
	v_mfma_f32_16x16x32_bf16 v[50:53], v[134:137], v[208:211], v[50:53]
	v_mfma_f32_16x16x32_bf16 v[42:45], v[142:145], v[208:211], v[42:45]
	v_mfma_f32_16x16x32_bf16 v[34:37], v[134:137], v[216:219], v[34:37]
	v_mfma_f32_16x16x32_bf16 v[26:29], v[142:145], v[216:219], v[26:29]
	v_mfma_f32_16x16x32_bf16 v[18:21], v[134:137], v[224:227], v[18:21]
	v_mfma_f32_16x16x32_bf16 v[10:13], v[142:145], v[224:227], v[10:13]
	s_setprio 0
	s_setprio 1
	v_mfma_f32_16x16x32_bf16 v[54:57], v[156:159], v[182:185], v[54:57]
	v_mfma_f32_16x16x32_bf16 v[46:49], v[172:175], v[182:185], v[46:49]
	v_mfma_f32_16x16x32_bf16 v[38:41], v[156:159], v[204:207], v[38:41]
	v_mfma_f32_16x16x32_bf16 v[30:33], v[172:175], v[204:207], v[30:33]
	v_mfma_f32_16x16x32_bf16 v[22:25], v[156:159], v[212:215], v[22:25]
	v_mfma_f32_16x16x32_bf16 v[14:17], v[172:175], v[212:215], v[14:17]
	v_mfma_f32_16x16x32_bf16 v[6:9], v[156:159], v[220:223], v[6:9]
	v_mfma_f32_16x16x32_bf16 v[2:5], v[172:175], v[220:223], v[2:5]
	v_mfma_f32_16x16x32_bf16 v[54:57], v[164:167], v[200:203], v[54:57]
	v_mfma_f32_16x16x32_bf16 v[46:49], v[178:181], v[200:203], v[46:49]
	v_mfma_f32_16x16x32_bf16 v[38:41], v[164:167], v[208:211], v[38:41]
	v_mfma_f32_16x16x32_bf16 v[30:33], v[178:181], v[208:211], v[30:33]
	v_mfma_f32_16x16x32_bf16 v[22:25], v[164:167], v[216:219], v[22:25]
	v_mfma_f32_16x16x32_bf16 v[14:17], v[178:181], v[216:219], v[14:17]
	v_mfma_f32_16x16x32_bf16 v[6:9], v[164:167], v[224:227], v[6:9]
	v_mfma_f32_16x16x32_bf16 v[2:5], v[178:181], v[224:227], v[2:5]
	s_setprio 0
	s_barrier
	s_add_i32 s39, s39, 2
	s_add_u32 s0, s0, 0x100
	s_addc_u32 s1, s1, 0
	s_add_u32 s37, s37, 0x100
	s_addc_u32 s38, s38, 0
	s_cmp_gt_u32 s39, 5
	s_cbranch_scc0 .LBB0_745
	s_and_b64 vcc, exec, s[6:7]
	s_cbranch_vccz .LBB0_748
	s_barrier
